# P4 start: the per-XCD scan-unit atomic is issued at phase 3 entry (result kept in v210), phase 4 only reads it
# baseline (speedup 1.0000x reference)
.LBB0_452:
	s_and_b64 vcc, exec, s[0:1]
	s_cbranch_vccz .LBB0_552
	v_readfirstlane_b32 s12, v166
	v_cmp_gt_i32_e32 vcc, 12, v166
	s_waitcnt vmcnt(0) lgkmcnt(0)
	s_barrier
	s_and_saveexec_b64 s[0:1], vcc
	v_lshl_add_u32 v0, v166, 2, 0
	v_add_u32_e32 v0, 0x15000, v0
	ds_write_b32 v0, v1
	s_or_b64 exec, exec, s[0:1]
	v_cmp_eq_u32_e32 vcc, 0, v166
	s_and_saveexec_b64 s[0:1], vcc
	s_cbranch_execz .Lxu_skip
	s_getreg_b32 s13, hwreg(HW_REG_XCC_ID, 0, 4)
	v_lshl_add_u32 v3, s13, 5, v210
	v_mov_b32_e32 v2, 0x15030
	ds_write_b32 v2, v3

.LBB0_556:
	s_or_b64 exec, exec, s[0:1]
	v_cmp_gt_u32_e32 vcc, 12, v166
	s_and_saveexec_b64 s[0:1], vcc
	v_readlane_b32 s12, v255, 13
	s_add_u32 s38, s24, 0x4a80000
	s_addc_u32 s39, s25, 0
	s_mul_i32 s12, s12, 48
	v_lshl_add_u32 v2, v166, 2, s12
	global_store_dword v2, v1, s[38:39]
	s_or_b64 exec, exec, s[0:1]
	v_cmp_eq_u32_e32 vcc, 0, v166
	s_and_saveexec_b64 s[0:1], vcc
	s_getreg_b32 s12, hwreg(HW_REG_XCC_ID, 0, 4)
	s_lshl_b32 s12, s12, 2
	s_add_u32 s38, s24, 0x5016000
	s_addc_u32 s39, s25, 0
	v_mov_b32_e32 v2, s12
	v_mov_b32_e32 v210, 1
	global_atomic_add v210, v2, v210, s[38:39] sc0
	s_or_b64 exec, exec, s[0:1]
	v_readlane_b32 s0, v250, 4
	v_readlane_b32 s1, v250, 5
	s_andn2_b64 vcc, exec, s[0:1]
	s_mov_b32 s66, 0x3d000
	s_movk_i32 s67, 0x207f
	s_movk_i32 s68, 0x7f
	s_cbranch_vccnz .LBB0_583
	v_readlane_b32 s0, v250, 46
	v_readlane_b32 s1, v250, 47
	s_andn2_b64 vcc, exec, s[0:1]
	v_readfirstlane_b32 s52, v166
	s_cbranch_vccnz .LBB0_582
	v_readlane_b32 s12, v250, 48
	v_readlane_b32 s13, v250, 49
	v_readlane_b32 s38, v254, 20
	v_readlane_b32 s46, v250, 52
	s_mov_b64 s[0:1], 0x6917000
	s_mov_b32 s62, 1
	s_andn2_b64 vcc, exec, s[12:13]
	v_readlane_b32 s39, v254, 21
	s_mov_b32 s61, s38
	v_readlane_b32 s58, v250, 51
	v_readlane_b32 s47, v250, 53
	s_cbranch_vccnz .LBB0_560
	v_readlane_b32 s38, v253, 32
	v_readlane_b32 s12, v253, 28
	v_readlane_b32 s46, v253, 30
	s_mov_b64 s[0:1], 0x5017000
	s_mov_b32 s62, 0
	v_readlane_b32 s39, v253, 33
	s_mov_b32 s61, s38
	s_mov_b32 s58, s12
	v_readlane_b32 s47, v253, 31
	v_readlane_b32 s13, v253, 29
